# P2: the 32 workgroups with 3 prompt attention units take no prompt chunk summaries; the other 208 share all 1024 (stride 208)
# speedup vs baseline: 1.0036x; 1.0036x over previous
; DI float log2_gamma(int h) { return log2f(1.0f - exp2f(-5.0f - (float)h)); }
; DI void retkv_load(const bf16_t* Z, int ru, int tid, KvRegs& R) {
;     bool samp; int b, c, h, row0; ret_decode(ru, samp, b, c, h, row0);
; #pragma unroll
;     for (int i = 0; i < 2; ++i) { const int v = tid + 512 * i, j = v >> 4, d0 = (v & 15) * 8; const bf16_t* zr = Z + (size_t)(row0 + j) * INW;
;         R.k[i] = *(const u32x4*)(zr + 1280 + 128 * h + d0); R.v[i] = *(const u32x4*)(zr + 1792 + 128 * h + d0); }
; }
; DI void retkv_loop(lds_t* lds, const Params& P, int u_lo, int u_hi, int first, int G, int tid, int wave, int lane) {
;     const bf16_t* Z = (const bf16_t*)(P.ws + WS_Z);
;     KvRegs R; int u = u_lo + first;
;     if (u < u_hi) retkv_load(Z, u, tid, R);
;     for (; u < u_hi; u += G) {
;         bool samp; int b, c, h, row0; ret_decode(u, samp, b, c, h, row0);
;         const float l2g = log2_gamma(h);
;         retkv_stage(lds, l2g, tid, R);
;         __syncthreads();
;         if (u + G < u_hi) retkv_load(Z, u + G, tid, R);
;         retkv_compute(lds, P, samp, b, c, h, l2g, wave, lane);
;         __syncthreads();
;     }
; }
.LBB0_586:
	s_cmpk_lt_i32 s3, 32
	s_cbranch_scc1 .LBB0_591
	s_sub_i32 s3, s3, 32
	s_movk_i32 s98, 0x30
	s_movk_i32 s101, 0xd0
	s_not_b32 s0, s3
	s_add_i32 s0, s101, s0
	s_cmpk_gt_i32 s0, 0x3ff
	s_cbranch_scc1 .LBB0_591
	s_lshl_b32 s1, s0, 4
	s_and_b32 s5, s1, 0xffffffc0
	v_ashrrev_i32_e32 v22, 4, v112
	s_waitcnt vmcnt(0)
	v_add_u32_e32 v0, s5, v22
	s_movk_i32 s4, 0x1600
	v_mov_b64_e32 v[8:9], s[74:75]
	s_lshl_b32 s0, s0, 8
	v_and_b32_e32 v18, 0x78, v114
	s_mov_b32 s1, 0
	s_waitcnt lgkmcnt(0)
	v_mad_i64_i32 v[0:1], s[6:7], v0, s4, v[8:9]
	s_and_b32 s0, s0, 0x300
	v_mov_b32_e32 v17, 0
	v_lshl_add_u64 v[0:1], v[0:1], 0, s[0:1]
	v_lshlrev_b32_e32 v16, 1, v18
	v_lshl_add_u64 v[10:11], v[0:1], 0, v[16:17]
	global_load_dwordx4 v[0:3], v[10:11], off offset:2560
	global_load_dwordx4 v[4:7], v[10:11], off offset:3584
	v_add_u32_e32 v10, 0x200, v112
	v_ashrrev_i32_e32 v23, 4, v10
	v_add_u32_e32 v10, s5, v23
	v_mad_i64_i32 v[8:9], s[6:7], v10, s4, v[8:9]
	v_lshl_add_u64 v[8:9], v[8:9], 0, s[0:1]
	v_lshl_add_u64 v[12:13], v[8:9], 0, v[16:17]
	global_load_dwordx4 v[8:11], v[12:13], off offset:2560
	s_nop 0
	global_load_dwordx4 v[12:15], v[12:13], off offset:3584
	v_bfe_u32 v20, v112, 2, 2
	v_lshrrev_b32_e32 v26, 1, v112
	s_movk_i32 s0, 0x110
	v_and_or_b32 v20, v26, 24, v20
	v_lshlrev_b32_e32 v26, 3, v113
	v_mul_lo_u32 v21, v22, s0
	v_mul_lo_u32 v30, v23, s0
	v_and_b32_e32 v26, 24, v26
	s_add_i32 s0, s65, 0
	v_lshlrev_b32_e32 v16, 4, v112
	v_add_u32_e32 v31, s0, v26
	v_readlane_b32 s0, v255, 13
	v_and_b32_e32 v16, 0xf0, v16
	s_lshl_b32 s0, s0, 4
	v_add_u32_e32 v19, 0, v16
	v_sub_u32_e32 v16, 63, v22
	s_add_u32 s5, s68, 0x9a00000
	v_cvt_f32_i32_e32 v24, v16
	v_sub_u32_e32 v16, 63, v23
	s_addc_u32 s6, s69, 0
	s_lshl_b32 s9, s96, 1
	v_cvt_f32_i32_e32 v25, v16
	s_add_i32 s12, s9, -1
	v_lshrrev_b32_e32 v16, 2, v112
	v_mul_u32_u24_e32 v33, 0x110, v20
	v_lshlrev_b32_e32 v20, 7, v112
	s_sub_i32 s8, 0, s3
	s_sub_i32 s3, s12, s3
	s_lshl_b32 s13, s98, 1
	s_lshl_b32 s9, s96, 4
	s_lshl_b32 s11, s98, 4
	v_add_u32_e32 v32, 0, v26
	v_and_b32_e32 v20, 0x780, v20
	v_and_b32_e32 v16, 12, v16
	s_not_b32 s7, s98
	s_sub_i32 s10, s3, s13
	s_sub_i32 s9, s9, s11
	s_lshl_b32 s11, s96, 7
	s_lshl_b32 s14, s98, 7
	s_add_i32 s7, s7, s96
	s_lshl_b32 s3, s10, 4
	s_lshl_b32 s10, s10, 7
	s_sub_i32 s11, s11, s14
	s_sub_i32 s12, s12, s13
	s_mov_b32 s13, 0xc2fc0000
	v_mov_b32_e32 v26, 0x42800000
	s_mov_b32 s14, 0x800000
	v_mov_b32_e32 v27, 0x42000000
	v_not_b32_e32 v28, 63
	v_add_u32_e32 v29, v19, v21
	v_add_u32_e32 v30, v19, v30
	v_lshlrev_b32_e32 v18, 1, v18
	v_add_u32_e32 v31, v31, v33
	v_add_u32_e32 v32, v32, v33
	s_lshl_b32 s15, s0, 1
	v_lshlrev_b32_e32 v16, 1, v16
	v_lshlrev_b32_e32 v20, 1, v20
	s_movk_i32 s16, 0x2000
	s_movk_i32 s17, 0x4000
	s_movk_i32 s18, 0x6000
	s_branch .LBB0_589
; DI unsigned pk(float a, float b) { f32x2 v = {a, b}; bf16x2_t r = __builtin_convertvector(v, bf16x2_t); return __builtin_bit_cast(unsigned, r); }
; DI f32x4 mfma16(bf16x8 a, bf16x8 b, f32x4 c) { return __builtin_amdgcn_mfma_f32_16x16x32_bf16(a, b, c, 0, 0, 0); }
; DI float log2_gamma(int h) { return log2f(1.0f - exp2f(-5.0f - (float)h)); }
; DI void retkv_compute(lds_t* lds, const Params& P, bool samp, int b, int c, int h, float l2g, int wave, int lane) {
;     lds_t* Ks = lds; lds_t* Vs = lds + 64 * RSR;
;     f32x4 acc[8];
; #pragma unroll
;     for (int et = 0; et < 8; ++et) acc[et] = (f32x4){0.f, 0.f, 0.f, 0.f};
; #pragma unroll
;     for (int ks = 0; ks < 2; ++ks) {
;         const bf16x8 a = frag_T(Ks, RSR, 32 * ks, 16 * wave, lane);
; #pragma unroll
;         for (int et = 0; et < 8; ++et) acc[et] = mfma16(a, frag_T(Vs, RSR, 32 * ks, 16 * et, lane), acc[et]);
;     }
;     const int g = lane >> 4, l15 = lane & 15;
;     if (!samp) {
;         bf16_t* U = (bf16_t*)(P.ws + WS_US) + ((size_t)(b * 32 + c) * 4 + h) * 16384;
; #pragma unroll
;         for (int et = 0; et < 8; ++et) { u32x2 w = {pk(acc[et][0], acc[et][1]), pk(acc[et][2], acc[et][3])}; *(u32x2*)(U + (16 * et + l15) * 128 + 16 * wave + 4 * g) = w; }
; DI void retkv_loop(lds_t* lds, const Params& P, int u_lo, int u_hi, int first, int G, int tid, int wave, int lane) {
;     const bf16_t* Z = (const bf16_t*)(P.ws + WS_Z);
;     KvRegs R; int u = u_lo + first;
;     if (u < u_hi) retkv_load(Z, u, tid, R);
;     for (; u < u_hi; u += G) {
;         bool samp; int b, c, h, row0; ret_decode(u, samp, b, c, h, row0);
;         const float l2g = log2_gamma(h);
;         retkv_stage(lds, l2g, tid, R);
;         __syncthreads();
;         if (u + G < u_hi) retkv_load(Z, u + G, tid, R);
;         retkv_compute(lds, P, samp, b, c, h, l2g, wave, lane);
;         __syncthreads();
;     }
.LBB0_588:
	ds_read_b64_tr_b16 v[34:35], v31
	ds_read_b64_tr_b16 v[36:37], v31 offset:1088
	ds_read_b64_tr_b16 v[38:39], v32 offset:17408
	ds_read_b64_tr_b16 v[42:43], v32 offset:17440
	ds_read_b64_tr_b16 v[46:47], v32 offset:17472
	ds_read_b64_tr_b16 v[50:51], v32 offset:17504
	ds_read_b64_tr_b16 v[40:41], v32 offset:18496
	ds_read_b64_tr_b16 v[44:45], v32 offset:18528
	ds_read_b64_tr_b16 v[48:49], v32 offset:18560
	ds_read_b64_tr_b16 v[52:53], v32 offset:18592
	ds_read_b64_tr_b16 v[54:55], v31 offset:8704
	ds_read_b64_tr_b16 v[56:57], v31 offset:9792
	ds_read_b64_tr_b16 v[60:61], v32 offset:18624
	ds_read_b64_tr_b16 v[58:59], v32 offset:17536
	ds_read_b64_tr_b16 v[62:63], v32 offset:17568
	ds_read_b64_tr_b16 v[66:67], v32 offset:17600
	ds_read_b64_tr_b16 v[70:71], v32 offset:17632
	ds_read_b64_tr_b16 v[64:65], v32 offset:18656
	ds_read_b64_tr_b16 v[68:69], v32 offset:18688
	ds_read_b64_tr_b16 v[72:73], v32 offset:18720
	s_bfe_u32 s0, s20, 0x50002
	s_ashr_i32 s20, s20, 2
	s_waitcnt lgkmcnt(13)
	v_mfma_f32_16x16x32_bf16 v[38:41], v[34:37], v[38:41], 0
	ds_read_b64_tr_b16 v[74:75], v32 offset:27200
	s_andn2_b32 s20, s20, 31
	s_or_b32 s20, s20, s0
	s_waitcnt lgkmcnt(13)
	v_mfma_f32_16x16x32_bf16 v[42:45], v[34:37], v[42:45], 0
	s_ashr_i32 s21, s20, 31
	s_lshl_b64 s[20:21], s[20:21], 17
	s_add_u32 s0, s5, s20
	s_waitcnt lgkmcnt(12)
	v_mfma_f32_16x16x32_bf16 v[46:49], v[34:37], v[46:49], 0
	s_addc_u32 s20, s6, s21
	s_lshl_b32 s19, s19, 15
	s_add_u32 s0, s0, s19
	s_waitcnt lgkmcnt(11)
	v_mfma_f32_16x16x32_bf16 v[50:53], v[34:37], v[50:53], 0
	s_addc_u32 s19, s20, 0
	s_add_u32 s20, s0, s15
	s_addc_u32 s21, s19, 0
	s_waitcnt lgkmcnt(7)
	v_mfma_f32_16x16x32_bf16 v[58:61], v[34:37], v[58:61], 0
	v_mov_b32_e32 v21, v17
	s_add_i32 s8, s8, s101
	s_add_i32 s3, s3, s9
	s_waitcnt lgkmcnt(3)
	v_mfma_f32_16x16x32_bf16 v[62:65], v[34:37], v[62:65], 0
	s_add_i32 s10, s10, s11
	s_add_i32 s0, s7, s8
	s_cmpk_lt_i32 s0, 0x400
	s_waitcnt lgkmcnt(2)
	v_mfma_f32_16x16x32_bf16 v[66:69], v[34:37], v[66:69], 0
	s_waitcnt lgkmcnt(1)
	v_mfma_f32_16x16x32_bf16 v[34:37], v[34:37], v[70:73], 0
	ds_read_b64_tr_b16 v[72:73], v32 offset:26112
	ds_read_b64_tr_b16 v[76:77], v32 offset:26144
	ds_read_b64_tr_b16 v[80:81], v32 offset:26176
	ds_read_b64_tr_b16 v[84:85], v32 offset:26208
	ds_read_b64_tr_b16 v[78:79], v32 offset:27232
	ds_read_b64_tr_b16 v[82:83], v32 offset:27264
	ds_read_b64_tr_b16 v[86:87], v32 offset:27296
	s_waitcnt lgkmcnt(6)
	v_mfma_f32_16x16x32_bf16 v[38:41], v[54:57], v[72:75], v[38:41]
	s_waitcnt lgkmcnt(2)
	v_mfma_f32_16x16x32_bf16 v[42:45], v[54:57], v[76:79], v[42:45]
	s_waitcnt lgkmcnt(1)
	v_mfma_f32_16x16x32_bf16 v[46:49], v[54:57], v[80:83], v[46:49]
	ds_read_b64_tr_b16 v[70:71], v32 offset:26240
	ds_read_b64_tr_b16 v[74:75], v32 offset:26272
	ds_read_b64_tr_b16 v[78:79], v32 offset:26304
	ds_read_b64_tr_b16 v[82:83], v32 offset:26336
	v_cvt_pk_bf16_f32 v38, v38, v39
	v_cvt_pk_bf16_f32 v39, v40, v41
	s_waitcnt lgkmcnt(4)
	v_mfma_f32_16x16x32_bf16 v[50:53], v[54:57], v[84:87], v[50:53]
	ds_read_b64_tr_b16 v[72:73], v32 offset:27328
	ds_read_b64_tr_b16 v[76:77], v32 offset:27360
	ds_read_b64_tr_b16 v[80:81], v32 offset:27392
	ds_read_b64_tr_b16 v[84:85], v32 offset:27424
	s_waitcnt lgkmcnt(3)
	v_mfma_f32_16x16x32_bf16 v[58:61], v[54:57], v[70:73], v[58:61]
	s_waitcnt lgkmcnt(2)
	v_mfma_f32_16x16x32_bf16 v[62:65], v[54:57], v[74:77], v[62:65]
	s_waitcnt lgkmcnt(1)
	v_mfma_f32_16x16x32_bf16 v[66:69], v[54:57], v[78:81], v[66:69]
	s_waitcnt lgkmcnt(0)
	v_mfma_f32_16x16x32_bf16 v[34:37], v[54:57], v[82:85], v[34:37]
	v_lshl_add_u64 v[54:55], s[20:21], 0, v[16:17]
	v_lshl_add_u64 v[40:41], v[54:55], 0, v[20:21]
	global_store_dwordx2 v[40:41], v[38:39], off
	v_cvt_pk_bf16_f32 v38, v42, v43
	v_add_co_u32_e32 v42, vcc, s16, v40
	v_cvt_pk_bf16_f32 v39, v44, v45
	s_nop 0
	v_addc_co_u32_e32 v43, vcc, 0, v41, vcc
	global_store_dwordx2 v[42:43], v[38:39], off offset:-4096
	v_cvt_pk_bf16_f32 v38, v46, v47
	v_cvt_pk_bf16_f32 v39, v48, v49
	global_store_dwordx2 v[42:43], v[38:39], off
	v_add_co_u32_e32 v42, vcc, s17, v40
	v_cvt_pk_bf16_f32 v38, v50, v51
	v_cvt_pk_bf16_f32 v39, v52, v53
	v_addc_co_u32_e32 v43, vcc, 0, v41, vcc
	global_store_dwordx2 v[42:43], v[38:39], off offset:-4096
	v_cvt_pk_bf16_f32 v38, v58, v59
	v_cvt_pk_bf16_f32 v39, v60, v61
	global_store_dwordx2 v[42:43], v[38:39], off
	v_add_co_u32_e32 v42, vcc, s18, v40
	v_cvt_pk_bf16_f32 v38, v62, v63
	s_nop 0
	v_addc_co_u32_e32 v43, vcc, 0, v41, vcc
	v_cvt_pk_bf16_f32 v39, v64, v65
	v_cvt_pk_bf16_f32 v34, v34, v35
	v_cvt_pk_bf16_f32 v35, v36, v37
	v_add_co_u32_e32 v36, vcc, 0x7000, v40
	global_store_dwordx2 v[42:43], v[38:39], off offset:-4096
	v_cvt_pk_bf16_f32 v38, v66, v67
	v_cvt_pk_bf16_f32 v39, v68, v69
	v_addc_co_u32_e32 v37, vcc, 0, v41, vcc
	global_store_dwordx2 v[42:43], v[38:39], off
	global_store_dwordx2 v[36:37], v[34:35], off
	s_barrier
	s_cbranch_scc0 .LBB0_591
